# phase-0 tile deal balanced by bytes: GEMV blocks take 1 conversion tile, WinU-copy blocks 8, the rest ~12 (was round-robin)
# speedup vs baseline: 1.0124x; 1.0048x over previous
.LBB0_6:
	s_cmp_lg_u32 s22, 0
	s_cselect_b64 s[4:5], -1, 0
	s_cmp_lt_i32 s23, 1
	s_cselect_b64 s[6:7], -1, 0
	s_or_b64 s[4:5], s[4:5], s[6:7]
	v_mov_b32_e32 v148, 0
	s_and_b64 vcc, exec, s[4:5]
	v_mov_b32_e32 v146, 0
	s_cbranch_vccnz .LBB0_82
	s_mov_b32 s98, s2
	s_load_dword s99, s[0:1], 0x468
	s_load_dword s100, s[0:1], 0x458
	s_mov_b32 s101, 0
	s_waitcnt lgkmcnt(0)
	s_addk_i32 s100, 0x140
	s_cmpk_lg_u32 s99, 0x200
	s_cbranch_scc1 PREP_ENTRY
	s_cmpk_lt_u32 s2, 0x140
	s_cbranch_scc1 PREP_SPECIAL
	s_add_u32 s98, s2, 0x4c0
	s_movk_i32 s99, 0xc0
	s_branch PREP_ENTRY
PREP_SPECIAL:
	s_add_u32 s100, s2, 1
	s_mov_b32 s101, 1
PREP_ENTRY:
	s_mov_b32 s34, s100
	s_movk_i32 s3, 0x3ff
	v_and_b32_e32 v1, 0x3ff, v0
	s_movk_i32 s4, 0x140
	s_waitcnt lgkmcnt(0)
	s_cmp_ge_i32 s98, s34
	s_cbranch_scc1 .LBB0_31
	v_lshlrev_b32_e32 v2, 4, v1
	v_and_b32_e32 v4, 48, v2
	v_lshrrev_b32_e32 v36, 4, v1
	v_and_b32_e32 v3, 0x3fc, v1
	v_mul_u32_u24_e32 v6, 0x41, v4
	v_lshl_add_u32 v42, v6, 2, v3
	v_mul_u32_u24_e32 v3, 0xc0000, v36
	v_and_b32_e32 v6, 15, v1
	s_mov_b32 s35, s99
	s_load_dwordx8 s[8:15], s[0:1], 0x30
	s_load_dword s36, s[0:1], 0x1f4
	s_load_dword s37, s[0:1], 0x21c
	s_load_dword s38, s[0:1], 0x244
	s_load_dword s39, s[0:1], 0x26c
	s_load_dword s40, s[0:1], 0x294
	s_load_dword s41, s[0:1], 0x2bc
	s_load_dword s42, s[0:1], 0x2e4
	s_load_dword s43, s[0:1], 0x30c
	s_load_dword s44, s[0:1], 0x334
	s_load_dword s45, s[0:1], 0x35c
	s_load_dword s46, s[0:1], 0x384
	s_load_dword s47, s[0:1], 0x3ac
	s_load_dword s48, s[0:1], 0x3d4
	s_load_dword s49, s[0:1], 0x3fc
	s_load_dword s50, s[0:1], 0x424
	s_load_dword s51, s[0:1], 0x44c
	s_load_dwordx2 s[6:7], s[0:1], 0x88
	s_load_dword s52, s[0:1], 0x1cc
	s_load_dwordx2 s[16:17], s[0:1], 0xb8
	s_load_dwordx2 s[18:19], s[0:1], 0xa8
	v_mul_hi_u32_u24_e32 v7, 0xc0000, v36
	v_lshl_or_b32 v6, v6, 4, v3
	s_lshl_b32 s53, s98, 6
	s_waitcnt lgkmcnt(0)
	v_lshl_add_u64 v[24:25], s[12:13], 0, v[6:7]
	v_lshrrev_b32_e32 v3, 6, v1
	s_movk_i32 s12, 0xc00
	v_mov_b32_e32 v6, s53
	v_lshlrev_b32_e32 v34, 2, v1
	v_and_b32_e32 v38, 63, v1
	v_mad_u32_u24 v6, v3, s12, v6
	v_and_b32_e32 v35, 60, v34
	v_mov_b32_e32 v23, 0
	v_or_b32_e32 v45, v6, v38
	v_lshlrev_b32_e32 v3, 8, v3
	v_lshlrev_b32_e32 v6, 2, v38
	s_movk_i32 s12, 0x5000
	v_lshlrev_b32_e32 v5, 2, v35
	v_mul_u32_u24_e32 v9, 0x104, v36
	v_or3_b32 v46, v3, v6, s12
	v_mov_b32_e32 v3, v23
	v_mul_u32_u24_e32 v8, 0x500, v36
	v_lshlrev_b32_e32 v22, 3, v1
	v_lshl_add_u64 v[2:3], s[16:17], 0, v[2:3]
	s_mov_b64 s[12:13], 0x6000
	v_add_u32_e32 v48, v5, v9
	v_cmp_gt_u32_e64 s[4:5], s4, v1
	v_lshrrev_b32_e32 v37, 2, v1
	v_add_u32_e32 v39, 16, v36
	v_add_u32_e32 v40, 32, v36
	v_add_u32_e32 v41, 48, v36
	s_lshl_b32 s54, s35, 6
	v_lshlrev_b32_e32 v43, 8, v36
	v_add_u32_e32 v44, 0xffffff00, v1
	v_lshl_add_u64 v[26:27], s[18:19], 0, v[22:23]
	s_add_i32 s55, s98, 0xffffff40
	s_lshl_b32 s56, s98, 4
	s_lshl_b32 s57, s35, 4
	v_lshl_add_u64 v[28:29], v[2:3], 0, s[12:13]
	s_movk_i32 s58, 0x400
	s_mov_b32 s13, 0
	s_movk_i32 s59, 0x12ff
	s_movk_i32 s60, 0x3000
	s_movk_i32 s61, 0x6000
	s_mov_b32 s62, 0x9000
	v_add_u32_e32 v47, v5, v8
	v_add_u32_e32 v49, 0x1040, v48
	v_add_u32_e32 v50, 0x1048, v48
	v_lshlrev_b32_e32 v30, 1, v4
	s_movk_i32 s63, 0xc000
	s_movk_i32 s64, 0xe000
	s_movk_i32 s65, 0x1000
	s_mov_b64 s[24:25], 0x8000
	v_add_u32_e32 v51, 0x2080, v48
	v_add_u32_e32 v52, 0x2088, v48
	v_add_u32_e32 v53, 0x30c0, v48
	v_add_u32_e32 v54, 0x30c8, v48
	v_add_u32_e32 v55, 0x400, v42
	v_add_u32_e32 v56, 0x800, v42
	v_add_u32_e32 v57, 0xc00, v42
	s_mov_b32 s66, s98
	s_branch .LBB0_10

.LBB0_31:
	s_cmp_eq_u32 s101, 1
	s_cbranch_scc0 PREP_DONE
	s_mov_b32 s101, 2
	s_cmpk_lt_u32 s2, 0xc0
	s_cbranch_scc1 PREP_P1A
	s_add_u32 s98, s2, 0x140
	s_movk_i32 s99, 0x80
	s_movk_i32 s100, 0x600
	s_branch PREP_ENTRY
PREP_P1A:
	s_add_u32 s98, s2, 0x140
	s_movk_i32 s99, 0xc0
	s_movk_i32 s100, 0x200
	s_branch PREP_ENTRY
PREP_DONE:
	v_mov_b32_e32 v148, 0
	s_cmp_lt_i32 s23, 2
	v_mov_b32_e32 v146, 0
	s_cbranch_scc1 .LBB0_82
	s_waitcnt vmcnt(0)
	v_mov_b32_e32 v5, 0
	v_cmp_eq_u32_e32 vcc, 0, v1
	v_mov_b32_e32 v4, 0
	s_barrier
	s_and_saveexec_b64 s[4:5], vcc
	s_cbranch_execz .LBB0_79
	s_waitcnt vmcnt(0) expcnt(0) lgkmcnt(0)
	s_load_dwordx2 s[8:9], s[0:1], 0x468
	s_load_dword s3, s[0:1], 0x470
	s_add_u32 s6, s20, 0x200
	s_addc_u32 s7, s21, 0
	s_mov_b32 s26, 1
	s_waitcnt lgkmcnt(0)
	s_mul_i32 s8, s9, s8
	s_mul_i32 s3, s8, s3
	s_add_u32 s8, s20, 0x1000
	s_addc_u32 s9, s21, 0
	s_add_u32 s10, s20, 0x1100
	s_addc_u32 s11, s21, 0
	s_add_u32 s12, s20, 0x1200
	s_addc_u32 s13, s21, 0
	s_add_u32 s14, s20, 0x1300
	s_addc_u32 s15, s21, 0
	v_mov_b32_e32 v18, 0
	s_branch .LBB0_35

	.amdhsa_kernel _Z4mega6Paramsii
		.amdhsa_group_segment_fixed_size 81920
		.amdhsa_private_segment_fixed_size 0
		.amdhsa_kernarg_size 1384
		.amdhsa_user_sgpr_count 2
		.amdhsa_user_sgpr_dispatch_ptr 0
		.amdhsa_user_sgpr_queue_ptr 0
		.amdhsa_user_sgpr_kernarg_segment_ptr 1
		.amdhsa_user_sgpr_dispatch_id 0
		.amdhsa_user_sgpr_kernarg_preload_length 0
		.amdhsa_user_sgpr_kernarg_preload_offset 0
		.amdhsa_user_sgpr_private_segment_size 0
		.amdhsa_uses_dynamic_stack 0
		.amdhsa_enable_private_segment 0
		.amdhsa_system_sgpr_workgroup_id_x 1
		.amdhsa_system_sgpr_workgroup_id_y 0
		.amdhsa_system_sgpr_workgroup_id_z 0
		.amdhsa_system_sgpr_workgroup_info 0
		.amdhsa_system_vgpr_workitem_id 2
		.amdhsa_next_free_vgpr 256
		.amdhsa_next_free_sgpr 102
		.amdhsa_accum_offset 256
		.amdhsa_reserve_vcc 1
		.amdhsa_float_round_mode_32 0
		.amdhsa_float_round_mode_16_64 0
		.amdhsa_float_denorm_mode_32 3
		.amdhsa_float_denorm_mode_16_64 3
		.amdhsa_dx10_clamp 1
		.amdhsa_ieee_mode 1
		.amdhsa_fp16_overflow 0
		.amdhsa_tg_split 0
		.amdhsa_exception_fp_ieee_invalid_op 0
		.amdhsa_exception_fp_denorm_src 0
		.amdhsa_exception_fp_ieee_div_zero 0
		.amdhsa_exception_fp_ieee_overflow 0
		.amdhsa_exception_fp_ieee_underflow 0
		.amdhsa_exception_fp_ieee_inexact 0
		.amdhsa_exception_int_div_zero 0
	.end_amdhsa_kernel

amdhsa.kernels:
  - .agpr_count:     0
    .args:
      - .offset:         0
        .size:           1120
        .value_kind:     by_value
      - .offset:         1120
        .size:           4
        .value_kind:     by_value
      - .offset:         1124
        .size:           4
        .value_kind:     by_value
      - .offset:         1128
        .size:           4
        .value_kind:     hidden_block_count_x
      - .offset:         1132
        .size:           4
        .value_kind:     hidden_block_count_y
      - .offset:         1136
        .size:           4
        .value_kind:     hidden_block_count_z
      - .offset:         1140
        .size:           2
        .value_kind:     hidden_group_size_x
      - .offset:         1142
        .size:           2
        .value_kind:     hidden_group_size_y
      - .offset:         1144
        .size:           2
        .value_kind:     hidden_group_size_z
      - .offset:         1146
        .size:           2
        .value_kind:     hidden_remainder_x
      - .offset:         1148
        .size:           2
        .value_kind:     hidden_remainder_y
      - .offset:         1150
        .size:           2
        .value_kind:     hidden_remainder_z
      - .offset:         1168
        .size:           8
        .value_kind:     hidden_global_offset_x
      - .offset:         1176
        .size:           8
        .value_kind:     hidden_global_offset_y
      - .offset:         1184
        .size:           8
        .value_kind:     hidden_global_offset_z
      - .offset:         1192
        .size:           2
        .value_kind:     hidden_grid_dims
      - .offset:         1216
        .size:           8
        .value_kind:     hidden_multigrid_sync_arg
    .group_segment_fixed_size: 81920
    .kernarg_segment_align: 8
    .kernarg_segment_size: 1384
    .language:       OpenCL C
    .language_version:
      - 2
      - 0
    .max_flat_workgroup_size: 256
    .name:           _Z4mega6Paramsii
    .private_segment_fixed_size: 0
    .sgpr_count:     108
    .sgpr_spill_count: 0
    .symbol:         _Z4mega6Paramsii.kd
    .uniform_work_group_size: 1
    .uses_dynamic_stack: false
    .vgpr_count:     256
    .vgpr_spill_count: 0
    .wavefront_size: 64
